# unrolled MLA fast path + rescale test issued right after the row sum is final, prefetch-valid flag removed, loop control placed before the last two MFMAs
# speedup vs baseline: 1.0078x; 1.0010x over previous
.Lmla_fast_havek_e:
	s_add_i32 s34, s30, 2
	s_cmp_gt_u32 s34, s14
	s_cbranch_scc1 .Lmla_fast_d2_e
	s_and_b32 s8, s34, 2
	s_mulk_i32 s8, 0x6400
	s_add_i32 s34, s8, 0
	s_add_i32 s8, s34, s5
	s_mov_b32 m0, s8
	s_and_b64 vcc, exec, s[36:37]
	global_load_lds_dwordx4 v66, s[26:27]
	s_add_i32 m0, s8, 0x2000
	v_add_u32_e32 v66, v66, v134
	global_load_lds_dwordx4 v68, s[26:27]
	s_add_i32 m0, s8, 0x4000
	v_add_u32_e32 v68, v68, v136
	global_load_lds_dwordx4 v70, s[26:27]
	v_add_u32_e32 v70, v70, v138
	s_cbranch_vccnz .Lmla_fast_d2_e
	s_add_i32 m0, s34, 0x6000
	s_nop 0
	global_load_lds_dwordx4 v72, s[26:27]
	v_add_u32_e32 v72, v72, v140

.Lmla_fast_nodma_e:
	s_waitcnt lgkmcnt(0)
	v_mfma_f32_32x32x16_bf16 v[50:65], v[194:197], v[74:77], v[234:249]
	ds_read_b128 v[194:197], v0 offset:6656
	v_add_f32_e32 v254, v202, v203
	v_add_f32_e32 v255, v204, v205
	v_add_f32_e32 v254, v254, v206
	v_add_f32_e32 v255, v255, v207
	v_add_f32_e32 v254, v254, v208
	v_add_f32_e32 v255, v255, v209
	v_mfma_f32_32x32x16_bf16 v[50:65], v[150:153], v[78:81], v[50:65]
	ds_read_b128 v[150:153], v0 offset:6688
	v_add_f32_e32 v254, v254, v210
	v_add_f32_e32 v255, v255, v211
	v_add_f32_e32 v254, v254, v212
	v_add_f32_e32 v255, v255, v213
	v_add_f32_e32 v254, v254, v214
	v_add_f32_e32 v255, v255, v215
	v_mfma_f32_32x32x16_bf16 v[50:65], v[158:161], v[82:85], v[50:65]
	ds_read_b128 v[158:161], v0 offset:6720
	v_add_f32_e32 v254, v254, v216
	v_add_f32_e32 v255, v255, v217
	v_add_f32_e32 v254, v254, v218
	v_add_f32_e32 v255, v255, v219
	v_add_f32_e32 v254, v254, v220
	v_mfma_f32_32x32x16_bf16 v[50:65], v[162:165], v[86:89], v[50:65]
	ds_read_b128 v[162:165], v0 offset:6752
	v_add_f32_e32 v255, v255, v221
	v_add_f32_e32 v254, v254, v222
	v_add_f32_e32 v255, v255, v223
	v_add_f32_e32 v254, v254, v224
	v_add_f32_e32 v255, v255, v225
	v_mfma_f32_32x32x16_bf16 v[50:65], v[174:177], v[90:93], v[50:65]
	ds_read_b128 v[174:177], v0 offset:6784
	v_add_f32_e32 v254, v254, v226
	v_add_f32_e32 v255, v255, v227
	v_add_f32_e32 v254, v254, v228
	v_add_f32_e32 v255, v255, v229
	v_add_f32_e32 v254, v254, v230
	v_mfma_f32_32x32x16_bf16 v[50:65], v[178:181], v[94:97], v[50:65]
	ds_read_b128 v[178:181], v0 offset:6816
	v_add_f32_e32 v255, v255, v231
	v_add_f32_e32 v254, v254, v232
	v_add_f32_e32 v255, v255, v233
	v_add_f32_e32 v254, v254, v255
	v_add_f32_e32 v147, v147, v254
	v_cmp_lt_f32_e32 vcc, 0x44800000, v254
	s_waitcnt lgkmcnt(5)
	v_mfma_f32_32x32x16_bf16 v[34:49], v[194:197], v[74:77], v[234:249]
	ds_read_b64_tr_b16 v[126:127], v142 offset:13312
	ds_read_b64_tr_b16 v[128:129], v142 offset:14848
	ds_read_b64_tr_b16 v[124:125], v142 offset:14912
	ds_read_b64_tr_b16 v[122:123], v142 offset:13376
	s_waitcnt lgkmcnt(8)
	v_mfma_f32_32x32x16_bf16 v[34:49], v[150:153], v[78:81], v[34:49]
	ds_read_b64_tr_b16 v[118:119], v142 offset:16384
	ds_read_b64_tr_b16 v[120:121], v142 offset:17920
	ds_read_b64_tr_b16 v[116:117], v142 offset:17984
	ds_read_b64_tr_b16 v[114:115], v142 offset:16448
	s_waitcnt lgkmcnt(11)
	v_mfma_f32_32x32x16_bf16 v[34:49], v[158:161], v[82:85], v[34:49]
	ds_read_b64_tr_b16 v[110:111], v142 offset:19456
	ds_read_b64_tr_b16 v[112:113], v142 offset:20992
	ds_read_b64_tr_b16 v[108:109], v142 offset:21056
	ds_read_b64_tr_b16 v[106:107], v142 offset:19520
	s_waitcnt lgkmcnt(11)
	v_mfma_f32_32x32x16_bf16 v[34:49], v[162:165], v[86:89], v[34:49]
	ds_read_b64_tr_b16 v[102:103], v142 offset:22528
	ds_read_b64_tr_b16 v[104:105], v142 offset:24064
	ds_read_b64_tr_b16 v[100:101], v142 offset:24128
	ds_read_b64_tr_b16 v[98:99], v142 offset:22592
	v_mfma_f32_32x32x16_bf16 v[34:49], v[174:177], v[90:93], v[34:49]
	v_exp_f32_e32 v202, v50
	v_mfma_f32_32x32x16_bf16 v[34:49], v[178:181], v[94:97], v[34:49]
.Lmla_fast_nostag_e:
	v_exp_f32_e32 v203, v51
	v_exp_f32_e32 v204, v52
	v_exp_f32_e32 v205, v53
	v_exp_f32_e32 v206, v54
	v_exp_f32_e32 v207, v55
	v_exp_f32_e32 v208, v56
	v_exp_f32_e32 v209, v57
	v_exp_f32_e32 v210, v58
	v_exp_f32_e32 v211, v59
	v_exp_f32_e32 v212, v60
	v_exp_f32_e32 v213, v61
	v_exp_f32_e32 v214, v62
	v_exp_f32_e32 v215, v63
	v_exp_f32_e32 v216, v64
	v_exp_f32_e32 v217, v65
	s_cbranch_vccnz .Lmla_fast_rescale_e
.Lmla_fast_ok_e:
	v_cvt_pk_bf16_f32 v166, v202, v203
	v_cvt_pk_bf16_f32 v167, v204, v205
	v_cvt_pk_bf16_f32 v168, v206, v207
	v_cvt_pk_bf16_f32 v169, v208, v209
	s_waitcnt lgkmcnt(0)
	s_nop 0
	v_mfma_f32_32x32x16_bf16 v[18:33], v[126:129], v[166:169], v[18:33]
	s_add_i32 s8, s30, 1
	s_and_b32 s8, s8, 3
	s_mulk_i32 s8, 0x6400
	v_add3_u32 v0, s8, v143, v132
	v_add3_u32 v142, s8, v144, v145
	v_mfma_f32_32x32x16_bf16 v[2:17], v[122:125], v[166:169], v[2:17]
	v_cvt_pk_bf16_f32 v170, v210, v211
	v_cvt_pk_bf16_f32 v171, v212, v213
	v_cvt_pk_bf16_f32 v172, v214, v215
	v_cvt_pk_bf16_f32 v173, v216, v217
	v_exp_f32_e32 v218, v34
	v_exp_f32_e32 v219, v35
	v_mfma_f32_32x32x16_bf16 v[18:33], v[118:121], v[170:173], v[18:33]
	v_exp_f32_e32 v220, v36
	v_exp_f32_e32 v221, v37
	ds_read_b128 v[194:197], v0
	ds_read_b128 v[150:153], v0 offset:32
	v_mfma_f32_32x32x16_bf16 v[2:17], v[114:117], v[170:173], v[2:17]
	v_exp_f32_e32 v222, v38
	v_exp_f32_e32 v223, v39
	v_exp_f32_e32 v224, v40
	v_exp_f32_e32 v225, v41
	v_cvt_pk_bf16_f32 v166, v218, v219
	v_cvt_pk_bf16_f32 v167, v220, v221
	v_cvt_pk_bf16_f32 v168, v222, v223
	v_cvt_pk_bf16_f32 v169, v224, v225
	ds_read_b128 v[158:161], v0 offset:64
	ds_read_b128 v[162:165], v0 offset:96
	v_mfma_f32_32x32x16_bf16 v[18:33], v[110:113], v[166:169], v[18:33]
	v_exp_f32_e32 v226, v42
	v_exp_f32_e32 v227, v43
	v_exp_f32_e32 v228, v44
	v_mfma_f32_32x32x16_bf16 v[2:17], v[106:109], v[166:169], v[2:17]
	v_exp_f32_e32 v229, v45
	v_exp_f32_e32 v230, v46
	v_exp_f32_e32 v231, v47
	v_exp_f32_e32 v232, v48
	v_exp_f32_e32 v233, v49
	ds_read_b128 v[174:177], v0 offset:128
	ds_read_b128 v[178:181], v0 offset:160
	v_cvt_pk_bf16_f32 v170, v226, v227
	v_cvt_pk_bf16_f32 v171, v228, v229
	v_cvt_pk_bf16_f32 v172, v230, v231
	v_cvt_pk_bf16_f32 v173, v232, v233
	s_add_i32 s30, s30, 1
	s_add_i32 s31, s31, 64
	v_subrev_u32_e32 v146, 64, v146
	s_cmp_le_u32 s31, s4
	v_mfma_f32_32x32x16_bf16 v[18:33], v[102:105], v[170:173], v[18:33]
	v_mfma_f32_32x32x16_bf16 v[2:17], v[98:101], v[170:173], v[2:17]
	s_cbranch_scc0 .Lmla_fast_generic
.Lmla_fast_havek_o:
.Lmla_fast_nodma_o:
	s_waitcnt lgkmcnt(0)
	v_mfma_f32_32x32x16_bf16 v[50:65], v[194:197], v[74:77], v[234:249]
	ds_read_b128 v[194:197], v0 offset:6656
	v_add_f32_e32 v254, v202, v203
	v_add_f32_e32 v255, v204, v205
	v_add_f32_e32 v254, v254, v206
	v_add_f32_e32 v255, v255, v207
	v_add_f32_e32 v254, v254, v208
	v_add_f32_e32 v255, v255, v209
	v_mfma_f32_32x32x16_bf16 v[50:65], v[150:153], v[78:81], v[50:65]
	ds_read_b128 v[150:153], v0 offset:6688
	v_add_f32_e32 v254, v254, v210
	v_add_f32_e32 v255, v255, v211
	v_add_f32_e32 v254, v254, v212
	v_add_f32_e32 v255, v255, v213
	v_add_f32_e32 v254, v254, v214
	v_add_f32_e32 v255, v255, v215
	v_mfma_f32_32x32x16_bf16 v[50:65], v[158:161], v[82:85], v[50:65]
	ds_read_b128 v[158:161], v0 offset:6720
	v_add_f32_e32 v254, v254, v216
	v_add_f32_e32 v255, v255, v217
	v_add_f32_e32 v254, v254, v218
	v_add_f32_e32 v255, v255, v219
	v_add_f32_e32 v254, v254, v220
	v_mfma_f32_32x32x16_bf16 v[50:65], v[162:165], v[86:89], v[50:65]
	ds_read_b128 v[162:165], v0 offset:6752
	v_add_f32_e32 v255, v255, v221
	v_add_f32_e32 v254, v254, v222
	v_add_f32_e32 v255, v255, v223
	v_add_f32_e32 v254, v254, v224
	v_add_f32_e32 v255, v255, v225
	v_mfma_f32_32x32x16_bf16 v[50:65], v[174:177], v[90:93], v[50:65]
	ds_read_b128 v[174:177], v0 offset:6784
	v_add_f32_e32 v254, v254, v226
	v_add_f32_e32 v255, v255, v227
	v_add_f32_e32 v254, v254, v228
	v_add_f32_e32 v255, v255, v229
	v_add_f32_e32 v254, v254, v230
	v_mfma_f32_32x32x16_bf16 v[50:65], v[178:181], v[94:97], v[50:65]
	ds_read_b128 v[178:181], v0 offset:6816
	v_add_f32_e32 v255, v255, v231
	v_add_f32_e32 v254, v254, v232
	v_add_f32_e32 v255, v255, v233
	v_add_f32_e32 v254, v254, v255
	v_add_f32_e32 v147, v147, v254
	v_cmp_lt_f32_e32 vcc, 0x44800000, v254
	s_waitcnt lgkmcnt(5)
	v_mfma_f32_32x32x16_bf16 v[34:49], v[194:197], v[74:77], v[234:249]
	ds_read_b64_tr_b16 v[126:127], v142 offset:13312
	ds_read_b64_tr_b16 v[128:129], v142 offset:14848
	ds_read_b64_tr_b16 v[124:125], v142 offset:14912
	ds_read_b64_tr_b16 v[122:123], v142 offset:13376
	s_waitcnt lgkmcnt(8)
	v_mfma_f32_32x32x16_bf16 v[34:49], v[150:153], v[78:81], v[34:49]
	ds_read_b64_tr_b16 v[118:119], v142 offset:16384
	ds_read_b64_tr_b16 v[120:121], v142 offset:17920
	ds_read_b64_tr_b16 v[116:117], v142 offset:17984
	ds_read_b64_tr_b16 v[114:115], v142 offset:16448
	s_waitcnt lgkmcnt(11)
	v_mfma_f32_32x32x16_bf16 v[34:49], v[158:161], v[82:85], v[34:49]
	ds_read_b64_tr_b16 v[110:111], v142 offset:19456
	ds_read_b64_tr_b16 v[112:113], v142 offset:20992
	ds_read_b64_tr_b16 v[108:109], v142 offset:21056
	ds_read_b64_tr_b16 v[106:107], v142 offset:19520
	s_waitcnt lgkmcnt(11)
	v_mfma_f32_32x32x16_bf16 v[34:49], v[162:165], v[86:89], v[34:49]
	ds_read_b64_tr_b16 v[102:103], v142 offset:22528
	ds_read_b64_tr_b16 v[104:105], v142 offset:24064
	ds_read_b64_tr_b16 v[100:101], v142 offset:24128
	ds_read_b64_tr_b16 v[98:99], v142 offset:22592
	v_mfma_f32_32x32x16_bf16 v[34:49], v[174:177], v[90:93], v[34:49]
	v_exp_f32_e32 v202, v50
	v_mfma_f32_32x32x16_bf16 v[34:49], v[178:181], v[94:97], v[34:49]
	s_waitcnt vmcnt(0) lgkmcnt(0)
	s_barrier

.Lmla_fast_ok_o:
	v_cvt_pk_bf16_f32 v166, v202, v203
	v_cvt_pk_bf16_f32 v167, v204, v205
	v_cvt_pk_bf16_f32 v168, v206, v207
	v_cvt_pk_bf16_f32 v169, v208, v209
	s_waitcnt lgkmcnt(0)
	s_nop 0
	v_mfma_f32_32x32x16_bf16 v[18:33], v[126:129], v[166:169], v[18:33]
	s_add_i32 s8, s30, 1
	s_and_b32 s8, s8, 3
	s_mulk_i32 s8, 0x6400
	v_add3_u32 v0, s8, v143, v132
	v_add3_u32 v142, s8, v144, v145
	v_mfma_f32_32x32x16_bf16 v[2:17], v[122:125], v[166:169], v[2:17]
	v_cvt_pk_bf16_f32 v170, v210, v211
	v_cvt_pk_bf16_f32 v171, v212, v213
	v_cvt_pk_bf16_f32 v172, v214, v215
	v_cvt_pk_bf16_f32 v173, v216, v217
	v_exp_f32_e32 v218, v34
	v_exp_f32_e32 v219, v35
	v_mfma_f32_32x32x16_bf16 v[18:33], v[118:121], v[170:173], v[18:33]
	v_exp_f32_e32 v220, v36
	v_exp_f32_e32 v221, v37
	ds_read_b128 v[194:197], v0
	ds_read_b128 v[150:153], v0 offset:32
	v_mfma_f32_32x32x16_bf16 v[2:17], v[114:117], v[170:173], v[2:17]
	v_exp_f32_e32 v222, v38
	v_exp_f32_e32 v223, v39
	v_exp_f32_e32 v224, v40
	v_exp_f32_e32 v225, v41
	v_cvt_pk_bf16_f32 v166, v218, v219
	v_cvt_pk_bf16_f32 v167, v220, v221
	v_cvt_pk_bf16_f32 v168, v222, v223
	v_cvt_pk_bf16_f32 v169, v224, v225
	ds_read_b128 v[158:161], v0 offset:64
	ds_read_b128 v[162:165], v0 offset:96
	v_mfma_f32_32x32x16_bf16 v[18:33], v[110:113], v[166:169], v[18:33]
	v_exp_f32_e32 v226, v42
	v_exp_f32_e32 v227, v43
	v_exp_f32_e32 v228, v44
	v_mfma_f32_32x32x16_bf16 v[2:17], v[106:109], v[166:169], v[2:17]
	v_exp_f32_e32 v229, v45
	v_exp_f32_e32 v230, v46
	v_exp_f32_e32 v231, v47
	v_exp_f32_e32 v232, v48
	v_exp_f32_e32 v233, v49
	ds_read_b128 v[174:177], v0 offset:128
	ds_read_b128 v[178:181], v0 offset:160
	v_cvt_pk_bf16_f32 v170, v226, v227
	v_cvt_pk_bf16_f32 v171, v228, v229
	v_cvt_pk_bf16_f32 v172, v230, v231
	v_cvt_pk_bf16_f32 v173, v232, v233
	s_add_i32 s30, s30, 1
	s_add_i32 s31, s31, 64
	v_subrev_u32_e32 v146, 64, v146
	s_cmp_le_u32 s31, s4
	v_mfma_f32_32x32x16_bf16 v[18:33], v[102:105], v[170:173], v[18:33]
	v_mfma_f32_32x32x16_bf16 v[2:17], v[98:101], v[170:173], v[2:17]
	s_cbranch_scc1 .Lmla_fast_havek_e
	s_branch .Lmla_fast_generic
